# attention steady loop: G-table prefetch plus the 32 bias subtracts as 16 v_pk_add_f32 (bit-identical), first paired measurement of this variant
# speedup vs baseline: 1.0039x; 1.0012x over previous
.LBB0_1341:
	v_sub_f32_e32 v0, v214, v217
	s_waitcnt lgkmcnt(4)
	v_pk_add_f32 v[110:111], v[0:1], v[222:223] op_sel_hi:[0,1] neg_lo:[0,1] neg_hi:[0,1]
	v_pk_add_f32 v[108:109], v[0:1], v[220:221] op_sel_hi:[0,1] neg_lo:[0,1] neg_hi:[0,1]
	v_pk_add_f32 v[106:107], v[0:1], v[198:199] op_sel_hi:[0,1] neg_lo:[0,1] neg_hi:[0,1]
	v_pk_add_f32 v[104:105], v[0:1], v[196:197] op_sel_hi:[0,1] neg_lo:[0,1] neg_hi:[0,1]
	v_pk_add_f32 v[102:103], v[0:1], v[194:195] op_sel_hi:[0,1] neg_lo:[0,1] neg_hi:[0,1]
	v_pk_add_f32 v[100:101], v[0:1], v[192:193] op_sel_hi:[0,1] neg_lo:[0,1] neg_hi:[0,1]
	v_pk_add_f32 v[98:99], v[0:1], v[190:191] op_sel_hi:[0,1] neg_lo:[0,1] neg_hi:[0,1]
	v_pk_add_f32 v[96:97], v[0:1], v[188:189] op_sel_hi:[0,1] neg_lo:[0,1] neg_hi:[0,1]
	s_waitcnt lgkmcnt(0)
	v_pk_add_f32 v[94:95], v[0:1], v[238:239] op_sel_hi:[0,1] neg_lo:[0,1] neg_hi:[0,1]
	v_pk_add_f32 v[92:93], v[0:1], v[236:237] op_sel_hi:[0,1] neg_lo:[0,1] neg_hi:[0,1]
	v_pk_add_f32 v[90:91], v[0:1], v[234:235] op_sel_hi:[0,1] neg_lo:[0,1] neg_hi:[0,1]
	v_pk_add_f32 v[88:89], v[0:1], v[232:233] op_sel_hi:[0,1] neg_lo:[0,1] neg_hi:[0,1]
	v_pk_add_f32 v[86:87], v[0:1], v[230:231] op_sel_hi:[0,1] neg_lo:[0,1] neg_hi:[0,1]
	v_pk_add_f32 v[84:85], v[0:1], v[228:229] op_sel_hi:[0,1] neg_lo:[0,1] neg_hi:[0,1]
	v_pk_add_f32 v[82:83], v[0:1], v[226:227] op_sel_hi:[0,1] neg_lo:[0,1] neg_hi:[0,1]
	v_pk_add_f32 v[80:81], v[0:1], v[224:225] op_sel_hi:[0,1] neg_lo:[0,1] neg_hi:[0,1]
	ds_read_b128 v[188:191], v180 offset:256
	ds_read_b128 v[192:195], v180 offset:288
	ds_read_b128 v[196:199], v180 offset:320
	ds_read_b128 v[220:223], v180 offset:352
	ds_read_b128 v[224:227], v180 offset:384
	ds_read_b128 v[228:231], v180 offset:416
	ds_read_b128 v[232:235], v180 offset:448
	ds_read_b128 v[236:239], v180 offset:480
	v_add_u32_e32 v0, s8, v216
	ds_read_b64_tr_b16 v[4:5], v0 offset:24576
	ds_read_b64_tr_b16 v[6:7], v0 offset:25088
	v_mfma_f32_32x32x16_bf16 v[96:111], v[172:175], v[124:127], v[96:111]
	v_add_f32_e32 v1, v64, v65
	v_add_f32_e32 v1, v66, v1
	v_add_f32_e32 v1, v67, v1
	v_add_f32_e32 v1, v68, v1
	v_add_f32_e32 v1, v69, v1
	v_cvt_pk_bf16_f32 v140, v64, v65
	v_cvt_pk_bf16_f32 v141, v66, v67
	ds_read_b64_tr_b16 v[8:9], v0 offset:28672
	ds_read_b64_tr_b16 v[10:11], v0 offset:29184
	v_mfma_f32_32x32x16_bf16 v[80:95], v[168:171], v[124:127], v[80:95]
	v_add_f32_e32 v1, v70, v1
	v_add_f32_e32 v1, v71, v1
	v_add_f32_e32 v1, v72, v1
	v_add_f32_e32 v1, v73, v1
	v_cvt_pk_bf16_f32 v142, v68, v69
	v_cvt_pk_bf16_f32 v143, v70, v71
	ds_read_b64_tr_b16 v[12:13], v0 offset:25600
	ds_read_b64_tr_b16 v[14:15], v0 offset:26112
	v_mfma_f32_32x32x16_bf16 v[96:111], v[164:167], v[120:123], v[96:111]
	v_add_f32_e32 v1, v74, v1
	v_add_f32_e32 v1, v75, v1
	v_add_f32_e32 v1, v76, v1
	v_add_f32_e32 v1, v77, v1
	v_cvt_pk_bf16_f32 v136, v72, v73
	v_cvt_pk_bf16_f32 v137, v74, v75
	ds_read_b64_tr_b16 v[64:65], v0 offset:29696
	ds_read_b64_tr_b16 v[66:67], v0 offset:30208
	v_mfma_f32_32x32x16_bf16 v[80:95], v[160:163], v[120:123], v[80:95]
	v_add_f32_e32 v1, v78, v1
	v_add_f32_e32 v1, v79, v1
	v_add_f32_e32 v1, v48, v1
	v_add_f32_e32 v1, v49, v1
	v_cvt_pk_bf16_f32 v138, v76, v77
	v_cvt_pk_bf16_f32 v139, v78, v79
	ds_read_b64_tr_b16 v[68:69], v0 offset:26624
	ds_read_b64_tr_b16 v[70:71], v0 offset:27136
	v_mfma_f32_32x32x16_bf16 v[96:111], v[156:159], v[116:119], v[96:111]
	v_add_f32_e32 v1, v50, v1
	v_add_f32_e32 v1, v51, v1
	v_add_f32_e32 v1, v52, v1
	v_add_f32_e32 v1, v53, v1
	v_cvt_pk_bf16_f32 v132, v48, v49
	v_cvt_pk_bf16_f32 v133, v50, v51
	ds_read_b64_tr_b16 v[48:49], v0 offset:30720
	ds_read_b64_tr_b16 v[50:51], v0 offset:31232
	v_mfma_f32_32x32x16_bf16 v[80:95], v[152:155], v[116:119], v[80:95]
	v_add_f32_e32 v1, v54, v1
	v_add_f32_e32 v1, v55, v1
	v_add_f32_e32 v1, v56, v1
	v_add_f32_e32 v1, v57, v1
	v_cvt_pk_bf16_f32 v134, v52, v53
	v_cvt_pk_bf16_f32 v135, v54, v55
	ds_read_b64_tr_b16 v[52:53], v0 offset:27648
	ds_read_b64_tr_b16 v[54:55], v0 offset:28160
	v_mfma_f32_32x32x16_bf16 v[96:111], v[148:151], v[112:115], v[96:111]
	v_add_f32_e32 v1, v58, v1
	v_add_f32_e32 v1, v59, v1
	v_add_f32_e32 v1, v60, v1
	v_add_f32_e32 v1, v61, v1
	v_cvt_pk_bf16_f32 v128, v56, v57
	v_cvt_pk_bf16_f32 v129, v58, v59
	ds_read_b64_tr_b16 v[56:57], v0 offset:31744
	ds_read_b64_tr_b16 v[58:59], v0 offset:32256
	v_mfma_f32_32x32x16_bf16 v[80:95], v[144:147], v[112:115], v[80:95]
	v_add_f32_e32 v0, v62, v1
	v_add_f32_e32 v0, v63, v0
	v_add_f32_e32 v2, 0, v0
	v_cvt_pk_bf16_f32 v130, v60, v61
	v_cvt_pk_bf16_f32 v131, v62, v63
	s_mov_b32 s8, 0xfffe0000
	s_mov_b32 s9, -1
	v_lshl_add_u64 v[0:1], v[178:179], 0, s[8:9]
	s_add_i32 s0, s16, s21
	s_mov_b32 s4, m0
	s_mov_b32 m0, s0
	s_nop 0
	global_load_lds_dwordx4 v[0:1], off
	s_mov_b32 m0, s4
	v_lshl_add_u64 v[0:1], v[176:177], 0, s[8:9]
	s_add_i32 s0, s14, s22
	s_mov_b32 s4, m0
	s_mov_b32 m0, s0
	s_nop 0
	global_load_lds_dwordx4 v[0:1], off
	s_mov_b32 m0, s4
	v_max_f32_e32 v0, v97, v97
	v_max_f32_e32 v1, v96, v96
	v_max_f32_e32 v0, v1, v0
	v_max3_f32 v1, v98, v99, v81
	v_max3_f32 v0, v0, v80, v82
	v_max3_f32 v0, v0, v83, v100
	v_max3_f32 v1, v1, v102, v103
	v_max3_f32 v0, v0, v101, v84
	v_max3_f32 v1, v1, v86, v87
	v_max3_f32 v0, v0, v85, v104
	v_max3_f32 v1, v1, v106, v107
	v_max3_f32 v0, v0, v105, v88
	v_max3_f32 v1, v1, v90, v91
	v_max3_f32 v0, v0, v89, v108
	v_max3_f32 v1, v1, v110, v111
	v_max3_f32 v60, v0, v109, v92
	v_max3_f32 v1, v1, v94, v95
	v_max3_f32 v1, v60, v93, v1
	v_add_f32_e32 v0, v218, v2
	v_mov_b32_e32 v2, v1
	s_nop 1
	v_permlane32_swap_b32_e32 v1, v2
	v_max_f32_e32 v2, v2, v2
	v_max_f32_e32 v1, v1, v1
	v_max_f32_e32 v1, v1, v2
	v_cmp_lt_f32_e32 vcc, s33, v1
	s_cmp_lg_u64 vcc, 0
	s_cselect_b64 s[8:9], -1, 0
	s_cbranch_vccnz .LBB0_1349

.LBB0_1344:
	s_add_i32 s0, s14, 0x2000
	s_cmpk_lg_i32 s14, 0x4000
	s_cselect_b32 s25, s0, 0
	v_sub_f32_e32 v1, v214, v217
	s_waitcnt lgkmcnt(4)
	v_pk_add_f32 v[78:79], v[0:1], v[222:223] op_sel:[1,0] op_sel_hi:[1,1] neg_lo:[0,1] neg_hi:[0,1]
	v_pk_add_f32 v[76:77], v[0:1], v[220:221] op_sel:[1,0] op_sel_hi:[1,1] neg_lo:[0,1] neg_hi:[0,1]
	v_pk_add_f32 v[74:75], v[0:1], v[198:199] op_sel:[1,0] op_sel_hi:[1,1] neg_lo:[0,1] neg_hi:[0,1]
	v_pk_add_f32 v[72:73], v[0:1], v[196:197] op_sel:[1,0] op_sel_hi:[1,1] neg_lo:[0,1] neg_hi:[0,1]
	v_pk_add_f32 v[70:71], v[0:1], v[194:195] op_sel:[1,0] op_sel_hi:[1,1] neg_lo:[0,1] neg_hi:[0,1]
	v_pk_add_f32 v[68:69], v[0:1], v[192:193] op_sel:[1,0] op_sel_hi:[1,1] neg_lo:[0,1] neg_hi:[0,1]
	v_pk_add_f32 v[66:67], v[0:1], v[190:191] op_sel:[1,0] op_sel_hi:[1,1] neg_lo:[0,1] neg_hi:[0,1]
	v_pk_add_f32 v[64:65], v[0:1], v[188:189] op_sel:[1,0] op_sel_hi:[1,1] neg_lo:[0,1] neg_hi:[0,1]
	s_waitcnt lgkmcnt(0)
	v_pk_add_f32 v[62:63], v[0:1], v[238:239] op_sel:[1,0] op_sel_hi:[1,1] neg_lo:[0,1] neg_hi:[0,1]
	v_pk_add_f32 v[60:61], v[0:1], v[236:237] op_sel:[1,0] op_sel_hi:[1,1] neg_lo:[0,1] neg_hi:[0,1]
	v_pk_add_f32 v[58:59], v[0:1], v[234:235] op_sel:[1,0] op_sel_hi:[1,1] neg_lo:[0,1] neg_hi:[0,1]
	v_pk_add_f32 v[56:57], v[0:1], v[232:233] op_sel:[1,0] op_sel_hi:[1,1] neg_lo:[0,1] neg_hi:[0,1]
	v_pk_add_f32 v[54:55], v[0:1], v[230:231] op_sel:[1,0] op_sel_hi:[1,1] neg_lo:[0,1] neg_hi:[0,1]
	v_pk_add_f32 v[52:53], v[0:1], v[228:229] op_sel:[1,0] op_sel_hi:[1,1] neg_lo:[0,1] neg_hi:[0,1]
	v_pk_add_f32 v[50:51], v[0:1], v[226:227] op_sel:[1,0] op_sel_hi:[1,1] neg_lo:[0,1] neg_hi:[0,1]
	v_pk_add_f32 v[48:49], v[0:1], v[224:225] op_sel:[1,0] op_sel_hi:[1,1] neg_lo:[0,1] neg_hi:[0,1]
	ds_read_b128 v[188:191], v180 offset:512
	ds_read_b128 v[192:195], v180 offset:544
	ds_read_b128 v[196:199], v180 offset:576
	ds_read_b128 v[220:223], v180 offset:608
	ds_read_b128 v[224:227], v180 offset:640
	ds_read_b128 v[228:231], v180 offset:672
	ds_read_b128 v[232:235], v180 offset:704
	ds_read_b128 v[236:239], v180 offset:736
	v_add_u32_e32 v1, s16, v216
	ds_read_b64_tr_b16 v[152:153], v1 offset:24576
	ds_read_b64_tr_b16 v[154:155], v1 offset:25088
	v_mfma_f32_32x32x16_bf16 v[64:79], v[164:167], v[124:127], v[64:79]
	v_add_f32_e32 v2, v96, v97
	v_add_f32_e32 v2, v98, v2
	v_add_f32_e32 v2, v99, v2
	v_add_f32_e32 v2, v100, v2
	v_add_f32_e32 v2, v101, v2
	v_cvt_pk_bf16_f32 v140, v96, v97
	v_cvt_pk_bf16_f32 v141, v98, v99
	ds_read_b64_tr_b16 v[96:97], v1 offset:28672
	ds_read_b64_tr_b16 v[98:99], v1 offset:29184
	v_mfma_f32_32x32x16_bf16 v[48:63], v[160:163], v[124:127], v[48:63]
	v_add_f32_e32 v2, v102, v2
	v_add_f32_e32 v2, v103, v2
	v_add_f32_e32 v2, v104, v2
	v_add_f32_e32 v2, v105, v2
	v_cvt_pk_bf16_f32 v142, v100, v101
	v_cvt_pk_bf16_f32 v143, v102, v103
	ds_read_b64_tr_b16 v[100:101], v1 offset:25600
	ds_read_b64_tr_b16 v[102:103], v1 offset:26112
	v_mfma_f32_32x32x16_bf16 v[64:79], v[156:159], v[120:123], v[64:79]
	v_add_f32_e32 v2, v106, v2
	v_add_f32_e32 v2, v107, v2
	v_add_f32_e32 v2, v108, v2
	v_add_f32_e32 v2, v109, v2
	v_cvt_pk_bf16_f32 v136, v104, v105
	v_cvt_pk_bf16_f32 v137, v106, v107
	ds_read_b64_tr_b16 v[104:105], v1 offset:29696
	ds_read_b64_tr_b16 v[106:107], v1 offset:30208
	v_mfma_f32_32x32x16_bf16 v[48:63], v[148:151], v[120:123], v[48:63]
	v_add_f32_e32 v2, v110, v2
	v_add_f32_e32 v2, v111, v2
	v_add_f32_e32 v2, v80, v2
	v_add_f32_e32 v2, v81, v2
	v_cvt_pk_bf16_f32 v138, v108, v109
	v_cvt_pk_bf16_f32 v139, v110, v111
	ds_read_b64_tr_b16 v[108:109], v1 offset:26624
	ds_read_b64_tr_b16 v[110:111], v1 offset:27136
	v_mfma_f32_32x32x16_bf16 v[64:79], v[144:147], v[116:119], v[64:79]
	v_add_f32_e32 v2, v82, v2
	v_add_f32_e32 v2, v83, v2
	v_add_f32_e32 v2, v84, v2
	v_add_f32_e32 v2, v85, v2
	v_cvt_pk_bf16_f32 v132, v80, v81
	v_cvt_pk_bf16_f32 v133, v82, v83
	ds_read_b64_tr_b16 v[80:81], v1 offset:30720
	ds_read_b64_tr_b16 v[82:83], v1 offset:31232
	v_mfma_f32_32x32x16_bf16 v[48:63], v[12:15], v[116:119], v[48:63]
	v_add_f32_e32 v2, v86, v2
	v_add_f32_e32 v2, v87, v2
	v_add_f32_e32 v2, v88, v2
	v_add_f32_e32 v2, v89, v2
	v_cvt_pk_bf16_f32 v134, v84, v85
	v_cvt_pk_bf16_f32 v135, v86, v87
	ds_read_b64_tr_b16 v[12:13], v1 offset:27648
	ds_read_b64_tr_b16 v[14:15], v1 offset:28160
	v_mfma_f32_32x32x16_bf16 v[64:79], v[8:11], v[112:115], v[64:79]
	v_add_f32_e32 v2, v90, v2
	v_add_f32_e32 v2, v91, v2
	v_add_f32_e32 v2, v92, v2
	v_add_f32_e32 v2, v93, v2
	v_cvt_pk_bf16_f32 v128, v88, v89
	v_cvt_pk_bf16_f32 v129, v90, v91
	ds_read_b64_tr_b16 v[8:9], v1 offset:31744
	ds_read_b64_tr_b16 v[10:11], v1 offset:32256
	v_mfma_f32_32x32x16_bf16 v[48:63], v[4:7], v[112:115], v[48:63]
	v_add_f32_e32 v1, v94, v2
	v_add_f32_e32 v1, v95, v1
	v_add_f32_e32 v1, 0, v1
	v_cvt_pk_bf16_f32 v130, v92, v93
	v_cvt_pk_bf16_f32 v131, v94, v95
	v_max_f32_e32 v2, v65, v65
	v_max_f32_e32 v4, v64, v64
	v_max_f32_e32 v2, v4, v2
	s_nop 3
	v_max3_f32 v4, v66, v67, v49
	v_max3_f32 v2, v2, v48, v50
	v_max3_f32 v2, v2, v51, v68
	v_max3_f32 v4, v4, v70, v71
	v_max3_f32 v2, v2, v69, v52
	v_max3_f32 v4, v4, v54, v55
	v_max3_f32 v2, v2, v53, v72
	v_max3_f32 v4, v4, v74, v75
	v_max3_f32 v2, v2, v73, v56
	v_max3_f32 v4, v4, v58, v59
	v_max3_f32 v2, v2, v57, v76
	v_max3_f32 v4, v4, v78, v79
	v_max3_f32 v2, v2, v77, v60
	v_max3_f32 v4, v4, v62, v63
	v_add_f32_e32 v218, v0, v1
	v_max3_f32 v0, v2, v61, v4
	v_mov_b32_e32 v1, v0
	s_nop 1
	v_permlane32_swap_b32_e32 v0, v1
	v_max_f32_e32 v1, v1, v1
	v_max_f32_e32 v0, v0, v0
	s_add_i32 s0, s14, s21
	s_mov_b32 s4, m0
	s_mov_b32 m0, s0
	s_nop 0
	global_load_lds_dwordx4 v[178:179], off
	s_mov_b32 m0, s4
	v_max_f32_e32 v0, v0, v1
	s_add_i32 s0, s25, s22
	s_mov_b32 s4, m0
	s_mov_b32 m0, s0
	s_nop 0
	global_load_lds_dwordx4 v[176:177], off
	s_mov_b32 m0, s4
	v_cmp_lt_f32_e32 vcc, s33, v0
	s_cmp_lg_u64 vcc, 0
	s_cselect_b64 s[8:9], -1, 0
	s_cbranch_vccnz .LBB0_1352
